# fused final epilogue: each pair of f32 stores (16-byte pieces over 16 rows) merged into two full-line stores (8 rows x 128 bytes) with DPP row shifts
# baseline (speedup 1.0000x reference)
; __device__ __forceinline__ void epi_final(f32x4 (&acc)[2][2][4][2], const Unit& u, int wr, int wc, int fr, int fq, const EpiArgs& E, LAS float* rt) {
;     ...
; #pragma unroll
;     for (int ai = 0; ai < 2; ++ai)
; #pragma unroll
;         for (int m = 0; m < 4; ++m) { const int row = rowb + ai * HALF + m * 16; const float r = rt[ai * HALF + wr * 64 + m * 16 + fr];
; #pragma unroll
;             for (int bj = 0; bj < 2; ++bj) { const int col = u.pn * BM + bj * HALF + wc * 32 + fq * 8;
;                 const f32x4 g0 = *(const f32x4*)(E.gfin + col), g1 = *(const f32x4*)(E.gfin + col + 4);
;                 __builtin_nontemporal_store(acc[ai][bj][m][0] * r * g0, (f32x4*)(E.yout + (size_t)row * 1024 + col));
;                 __builtin_nontemporal_store(acc[ai][bj][m][1] * r * g1, (f32x4*)(E.yout + (size_t)row * 1024 + col + 4)); } }
.LBB0_1441:
	s_or_b64 exec, exec, s[0:1]
	v_bfe_u32 v232, v0, 3, 1
	v_mul_u32_u24_e32 v240, 0x7ff0, v232
	v_sub_u32_e32 v242, 0x8000, v240
	v_sub_u32_e32 v240, 0, v240
	v_sub_u32_e32 v241, 0, v232
	v_mov_b32_e32 v243, 0
	v_lshlrev_b64 v[148:149], 2, v[132:133]
	v_lshl_add_u64 v[132:133], s[24:25], 0, v[148:149]
	s_waitcnt lgkmcnt(0)
	s_barrier
	s_waitcnt vmcnt(0)
	s_lshl_b32 s0, s47, 2
	s_add_i32 s0, s0, 0
	v_lshl_add_u32 v1, v1, 2, s0
	v_add_u32_e32 v1, 0x20010, v1
	ds_read2_b32 v[158:159], v1 offset1:16
	v_lshlrev_b64 v[130:131], 12, v[130:131]
	v_lshl_add_u64 v[130:131], s[28:29], 0, v[130:131]
	v_lshl_add_u64 v[130:131], v[130:131], 0, v[148:149]
	s_waitcnt lgkmcnt(0)
	v_pk_mul_f32 v[128:129], v[128:129], v[158:159] op_sel_hi:[1,0]
	v_pk_mul_f32 v[126:127], v[126:127], v[158:159] op_sel_hi:[1,0]
	v_pk_mul_f32 v[160:161], v[124:125], v[158:159] op_sel_hi:[1,0]
	v_pk_mul_f32 v[162:163], v[122:123], v[158:159] op_sel_hi:[1,0]
	v_pk_mul_f32 v[120:121], v[120:121], v[158:159] op_sel_hi:[1,0]
	v_pk_mul_f32 v[118:119], v[118:119], v[158:159] op_sel_hi:[1,0]
	v_pk_mul_f32 v[124:125], v[174:175], v[128:129]
	v_pk_mul_f32 v[122:123], v[172:173], v[126:127]
	v_pk_mul_f32 v[128:129], v[178:179], v[160:161]
	v_pk_mul_f32 v[126:127], v[176:177], v[162:163]
	v_mov_b32_e32 v232, v126
	v_mov_b32_e32 v233, v127
	v_mov_b32_e32 v234, v128
	v_mov_b32_e32 v235, v129
	v_mov_b32_dpp v232, v122 row_shl:8 row_mask:0xf bank_mask:0x3
	v_mov_b32_dpp v233, v123 row_shl:8 row_mask:0xf bank_mask:0x3
	v_mov_b32_dpp v234, v124 row_shl:8 row_mask:0xf bank_mask:0x3
	v_mov_b32_dpp v235, v125 row_shl:8 row_mask:0xf bank_mask:0x3
	v_mov_b32_dpp v122, v126 row_shr:8 row_mask:0xf bank_mask:0xc
	v_mov_b32_dpp v123, v127 row_shr:8 row_mask:0xf bank_mask:0xc
	v_mov_b32_dpp v124, v128 row_shr:8 row_mask:0xf bank_mask:0xc
	v_mov_b32_dpp v125, v129 row_shr:8 row_mask:0xf bank_mask:0xc
	v_lshl_add_u64 v[236:237], v[130:131], 0, v[240:241]
	v_lshl_add_u64 v[238:239], v[130:131], 0, v[242:243]
	global_store_dwordx4 v[236:237], v[122:125], off nt
	global_store_dwordx4 v[238:239], v[232:235], off nt
	v_pk_mul_f32 v[150:151], v[116:117], v[158:159] op_sel_hi:[1,0]
	v_pk_mul_f32 v[152:153], v[114:115], v[158:159] op_sel_hi:[1,0]
	v_pk_mul_f32 v[116:117], v[120:121], v[182:183]
	v_pk_mul_f32 v[114:115], v[118:119], v[180:181]
	v_pk_mul_f32 v[120:121], v[150:151], v[186:187]
	v_pk_mul_f32 v[118:119], v[152:153], v[184:185]
	v_mov_b32_e32 v232, v118
	v_mov_b32_e32 v233, v119
	v_mov_b32_e32 v234, v120
	v_mov_b32_e32 v235, v121
	v_mov_b32_dpp v232, v114 row_shl:8 row_mask:0xf bank_mask:0x3
	v_mov_b32_dpp v233, v115 row_shl:8 row_mask:0xf bank_mask:0x3
	v_mov_b32_dpp v234, v116 row_shl:8 row_mask:0xf bank_mask:0x3
	v_mov_b32_dpp v235, v117 row_shl:8 row_mask:0xf bank_mask:0x3
	v_mov_b32_dpp v114, v118 row_shr:8 row_mask:0xf bank_mask:0xc
	v_mov_b32_dpp v115, v119 row_shr:8 row_mask:0xf bank_mask:0xc
	v_mov_b32_dpp v116, v120 row_shr:8 row_mask:0xf bank_mask:0xc
	v_mov_b32_dpp v117, v121 row_shr:8 row_mask:0xf bank_mask:0xc
	v_lshl_add_u64 v[236:237], v[130:131], 0, v[240:241]
	v_lshl_add_u64 v[238:239], v[130:131], 0, v[242:243]
	global_store_dwordx4 v[236:237], v[114:117], off offset:512 nt
	global_store_dwordx4 v[238:239], v[232:235], off offset:512 nt
	v_lshlrev_b64 v[122:123], 12, v[134:135]
	v_mov_b32_e32 v124, v159
	v_lshl_add_u64 v[122:123], s[28:29], 0, v[122:123]
	v_pk_mul_f32 v[112:113], v[112:113], v[124:125] op_sel_hi:[1,0]
	v_pk_mul_f32 v[126:127], v[136:137], v[124:125] op_sel_hi:[1,0]
	v_lshl_add_u64 v[122:123], v[122:123], 0, v[148:149]
	v_pk_mul_f32 v[128:129], v[108:109], v[124:125] op_sel_hi:[1,0]
	v_pk_mul_f32 v[130:131], v[106:107], v[124:125] op_sel_hi:[1,0]
	v_pk_mul_f32 v[104:105], v[104:105], v[124:125] op_sel_hi:[1,0]
	v_pk_mul_f32 v[102:103], v[102:103], v[124:125] op_sel_hi:[1,0]
	v_pk_mul_f32 v[108:109], v[174:175], v[112:113]
	v_pk_mul_f32 v[106:107], v[172:173], v[126:127]
	v_pk_mul_f32 v[114:115], v[178:179], v[128:129]
	v_pk_mul_f32 v[112:113], v[176:177], v[130:131]
	v_mov_b32_e32 v232, v112
	v_mov_b32_e32 v233, v113
	v_mov_b32_e32 v234, v114
	v_mov_b32_e32 v235, v115
	v_mov_b32_dpp v232, v106 row_shl:8 row_mask:0xf bank_mask:0x3
	v_mov_b32_dpp v233, v107 row_shl:8 row_mask:0xf bank_mask:0x3
	v_mov_b32_dpp v234, v108 row_shl:8 row_mask:0xf bank_mask:0x3
	v_mov_b32_dpp v235, v109 row_shl:8 row_mask:0xf bank_mask:0x3
	v_mov_b32_dpp v106, v112 row_shr:8 row_mask:0xf bank_mask:0xc
	v_mov_b32_dpp v107, v113 row_shr:8 row_mask:0xf bank_mask:0xc
	v_mov_b32_dpp v108, v114 row_shr:8 row_mask:0xf bank_mask:0xc
	v_mov_b32_dpp v109, v115 row_shr:8 row_mask:0xf bank_mask:0xc
	v_lshl_add_u64 v[236:237], v[122:123], 0, v[240:241]
	v_lshl_add_u64 v[238:239], v[122:123], 0, v[242:243]
	global_store_dwordx4 v[236:237], v[106:109], off nt
	global_store_dwordx4 v[238:239], v[232:235], off nt
	v_pk_mul_f32 v[116:117], v[100:101], v[124:125] op_sel_hi:[1,0]
	v_pk_mul_f32 v[118:119], v[98:99], v[124:125] op_sel_hi:[1,0]
	v_pk_mul_f32 v[100:101], v[104:105], v[182:183]
	v_pk_mul_f32 v[98:99], v[102:103], v[180:181]
	v_pk_mul_f32 v[104:105], v[116:117], v[186:187]
	v_pk_mul_f32 v[102:103], v[118:119], v[184:185]
	v_mov_b32_e32 v232, v102
	v_mov_b32_e32 v233, v103
	v_mov_b32_e32 v234, v104
	v_mov_b32_e32 v235, v105
	v_mov_b32_dpp v232, v98 row_shl:8 row_mask:0xf bank_mask:0x3
	v_mov_b32_dpp v233, v99 row_shl:8 row_mask:0xf bank_mask:0x3
	v_mov_b32_dpp v234, v100 row_shl:8 row_mask:0xf bank_mask:0x3
	v_mov_b32_dpp v235, v101 row_shl:8 row_mask:0xf bank_mask:0x3
	v_mov_b32_dpp v98, v102 row_shr:8 row_mask:0xf bank_mask:0xc
	v_mov_b32_dpp v99, v103 row_shr:8 row_mask:0xf bank_mask:0xc
	v_mov_b32_dpp v100, v104 row_shr:8 row_mask:0xf bank_mask:0xc
	v_mov_b32_dpp v101, v105 row_shr:8 row_mask:0xf bank_mask:0xc
	v_lshl_add_u64 v[236:237], v[122:123], 0, v[240:241]
	v_lshl_add_u64 v[238:239], v[122:123], 0, v[242:243]
	global_store_dwordx4 v[236:237], v[98:101], off offset:512 nt
	global_store_dwordx4 v[238:239], v[232:235], off offset:512 nt
	ds_read2_b32 v[106:107], v1 offset0:32 offset1:48
	v_lshlrev_b64 v[108:109], 12, v[110:111]
	v_lshl_add_u64 v[108:109], s[28:29], 0, v[108:109]
	v_lshl_add_u64 v[108:109], v[108:109], 0, v[148:149]
	s_waitcnt lgkmcnt(0)
; __device__ __forceinline__ void epi_final(f32x4 (&acc)[2][2][4][2], const Unit& u, int wr, int wc, int fr, int fq, const EpiArgs& E, LAS float* rt) {
;     ...
;     for (int ai = 0; ai < 2; ++ai)
; #pragma unroll
;         for (int m = 0; m < 4; ++m) { const int row = rowb + ai * HALF + m * 16; const float r = rt[ai * HALF + wr * 64 + m * 16 + fr];
; #pragma unroll
;             for (int bj = 0; bj < 2; ++bj) { const int col = u.pn * BM + bj * HALF + wc * 32 + fq * 8;
;                 const f32x4 g0 = *(const f32x4*)(E.gfin + col), g1 = *(const f32x4*)(E.gfin + col + 4);
;                 __builtin_nontemporal_store(acc[ai][bj][m][0] * r * g0, (f32x4*)(E.yout + (size_t)row * 1024 + col));
;                 __builtin_nontemporal_store(acc[ai][bj][m][1] * r * g1, (f32x4*)(E.yout + (size_t)row * 1024 + col + 4)); } }
	v_pk_mul_f32 v[96:97], v[96:97], v[106:107] op_sel_hi:[1,0]
	v_pk_mul_f32 v[94:95], v[94:95], v[106:107] op_sel_hi:[1,0]
	v_pk_mul_f32 v[110:111], v[92:93], v[106:107] op_sel_hi:[1,0]
	v_pk_mul_f32 v[112:113], v[90:91], v[106:107] op_sel_hi:[1,0]
	v_pk_mul_f32 v[88:89], v[88:89], v[106:107] op_sel_hi:[1,0]
	v_pk_mul_f32 v[86:87], v[86:87], v[106:107] op_sel_hi:[1,0]
	v_pk_mul_f32 v[92:93], v[174:175], v[96:97]
	v_pk_mul_f32 v[90:91], v[172:173], v[94:95]
	v_pk_mul_f32 v[96:97], v[178:179], v[110:111]
	v_pk_mul_f32 v[94:95], v[176:177], v[112:113]
	v_mov_b32_e32 v232, v94
	v_mov_b32_e32 v233, v95
	v_mov_b32_e32 v234, v96
	v_mov_b32_e32 v235, v97
	v_mov_b32_dpp v232, v90 row_shl:8 row_mask:0xf bank_mask:0x3
	v_mov_b32_dpp v233, v91 row_shl:8 row_mask:0xf bank_mask:0x3
	v_mov_b32_dpp v234, v92 row_shl:8 row_mask:0xf bank_mask:0x3
	v_mov_b32_dpp v235, v93 row_shl:8 row_mask:0xf bank_mask:0x3
	v_mov_b32_dpp v90, v94 row_shr:8 row_mask:0xf bank_mask:0xc
	v_mov_b32_dpp v91, v95 row_shr:8 row_mask:0xf bank_mask:0xc
	v_mov_b32_dpp v92, v96 row_shr:8 row_mask:0xf bank_mask:0xc
	v_mov_b32_dpp v93, v97 row_shr:8 row_mask:0xf bank_mask:0xc
	v_lshl_add_u64 v[236:237], v[108:109], 0, v[240:241]
	v_lshl_add_u64 v[238:239], v[108:109], 0, v[242:243]
	global_store_dwordx4 v[236:237], v[90:93], off nt
	global_store_dwordx4 v[238:239], v[232:235], off nt
	v_pk_mul_f32 v[98:99], v[84:85], v[106:107] op_sel_hi:[1,0]
	v_pk_mul_f32 v[100:101], v[82:83], v[106:107] op_sel_hi:[1,0]
	v_pk_mul_f32 v[84:85], v[88:89], v[182:183]
	v_pk_mul_f32 v[82:83], v[86:87], v[180:181]
	v_pk_mul_f32 v[88:89], v[98:99], v[186:187]
	v_pk_mul_f32 v[86:87], v[100:101], v[184:185]
	v_mov_b32_e32 v232, v86
	v_mov_b32_e32 v233, v87
	v_mov_b32_e32 v234, v88
	v_mov_b32_e32 v235, v89
	v_mov_b32_dpp v232, v82 row_shl:8 row_mask:0xf bank_mask:0x3
	v_mov_b32_dpp v233, v83 row_shl:8 row_mask:0xf bank_mask:0x3
	v_mov_b32_dpp v234, v84 row_shl:8 row_mask:0xf bank_mask:0x3
	v_mov_b32_dpp v235, v85 row_shl:8 row_mask:0xf bank_mask:0x3
	v_mov_b32_dpp v82, v86 row_shr:8 row_mask:0xf bank_mask:0xc
	v_mov_b32_dpp v83, v87 row_shr:8 row_mask:0xf bank_mask:0xc
	v_mov_b32_dpp v84, v88 row_shr:8 row_mask:0xf bank_mask:0xc
	v_mov_b32_dpp v85, v89 row_shr:8 row_mask:0xf bank_mask:0xc
	v_lshl_add_u64 v[236:237], v[108:109], 0, v[240:241]
	v_lshl_add_u64 v[238:239], v[108:109], 0, v[242:243]
	global_store_dwordx4 v[236:237], v[82:85], off offset:512 nt
	global_store_dwordx4 v[238:239], v[232:235], off offset:512 nt
	v_lshlrev_b64 v[90:91], 12, v[138:139]
	v_mov_b32_e32 v92, v107
	v_lshl_add_u64 v[90:91], s[28:29], 0, v[90:91]
	v_pk_mul_f32 v[80:81], v[80:81], v[92:93] op_sel_hi:[1,0]
	v_pk_mul_f32 v[94:95], v[140:141], v[92:93] op_sel_hi:[1,0]
	v_lshl_add_u64 v[90:91], v[90:91], 0, v[148:149]
	v_pk_mul_f32 v[96:97], v[76:77], v[92:93] op_sel_hi:[1,0]
	v_pk_mul_f32 v[98:99], v[74:75], v[92:93] op_sel_hi:[1,0]
	v_pk_mul_f32 v[72:73], v[72:73], v[92:93] op_sel_hi:[1,0]
	v_pk_mul_f32 v[70:71], v[70:71], v[92:93] op_sel_hi:[1,0]
	v_pk_mul_f32 v[76:77], v[174:175], v[80:81]
	v_pk_mul_f32 v[74:75], v[172:173], v[94:95]
	v_pk_mul_f32 v[82:83], v[178:179], v[96:97]
	v_pk_mul_f32 v[80:81], v[176:177], v[98:99]
	v_mov_b32_e32 v232, v80
	v_mov_b32_e32 v233, v81
	v_mov_b32_e32 v234, v82
	v_mov_b32_e32 v235, v83
	v_mov_b32_dpp v232, v74 row_shl:8 row_mask:0xf bank_mask:0x3
	v_mov_b32_dpp v233, v75 row_shl:8 row_mask:0xf bank_mask:0x3
	v_mov_b32_dpp v234, v76 row_shl:8 row_mask:0xf bank_mask:0x3
	v_mov_b32_dpp v235, v77 row_shl:8 row_mask:0xf bank_mask:0x3
	v_mov_b32_dpp v74, v80 row_shr:8 row_mask:0xf bank_mask:0xc
	v_mov_b32_dpp v75, v81 row_shr:8 row_mask:0xf bank_mask:0xc
	v_mov_b32_dpp v76, v82 row_shr:8 row_mask:0xf bank_mask:0xc
	v_mov_b32_dpp v77, v83 row_shr:8 row_mask:0xf bank_mask:0xc
	v_lshl_add_u64 v[236:237], v[90:91], 0, v[240:241]
	v_lshl_add_u64 v[238:239], v[90:91], 0, v[242:243]
	global_store_dwordx4 v[236:237], v[74:77], off nt
	global_store_dwordx4 v[238:239], v[232:235], off nt
	v_pk_mul_f32 v[84:85], v[68:69], v[92:93] op_sel_hi:[1,0]
	v_pk_mul_f32 v[86:87], v[66:67], v[92:93] op_sel_hi:[1,0]
	v_pk_mul_f32 v[68:69], v[72:73], v[182:183]
	v_pk_mul_f32 v[66:67], v[70:71], v[180:181]
	v_pk_mul_f32 v[72:73], v[84:85], v[186:187]
	v_pk_mul_f32 v[70:71], v[86:87], v[184:185]
	v_mov_b32_e32 v232, v70
	v_mov_b32_e32 v233, v71
	v_mov_b32_e32 v234, v72
	v_mov_b32_e32 v235, v73
	v_mov_b32_dpp v232, v66 row_shl:8 row_mask:0xf bank_mask:0x3
	v_mov_b32_dpp v233, v67 row_shl:8 row_mask:0xf bank_mask:0x3
	v_mov_b32_dpp v234, v68 row_shl:8 row_mask:0xf bank_mask:0x3
	v_mov_b32_dpp v235, v69 row_shl:8 row_mask:0xf bank_mask:0x3
	v_mov_b32_dpp v66, v70 row_shr:8 row_mask:0xf bank_mask:0xc
	v_mov_b32_dpp v67, v71 row_shr:8 row_mask:0xf bank_mask:0xc
	v_mov_b32_dpp v68, v72 row_shr:8 row_mask:0xf bank_mask:0xc
	v_mov_b32_dpp v69, v73 row_shr:8 row_mask:0xf bank_mask:0xc
	v_lshl_add_u64 v[236:237], v[90:91], 0, v[240:241]
	v_lshl_add_u64 v[238:239], v[90:91], 0, v[242:243]
	global_store_dwordx4 v[236:237], v[66:69], off offset:512 nt
	global_store_dwordx4 v[238:239], v[232:235], off offset:512 nt
	ds_read2_b32 v[74:75], v1 offset0:128 offset1:144
	v_lshlrev_b64 v[76:77], 12, v[78:79]
	v_lshl_add_u64 v[76:77], s[28:29], 0, v[76:77]
	v_lshl_add_u64 v[76:77], v[76:77], 0, v[148:149]
	s_waitcnt lgkmcnt(0)
; __device__ __forceinline__ void epi_final(f32x4 (&acc)[2][2][4][2], const Unit& u, int wr, int wc, int fr, int fq, const EpiArgs& E, LAS float* rt) {
;     ...
;     for (int ai = 0; ai < 2; ++ai)
; #pragma unroll
;         for (int m = 0; m < 4; ++m) { const int row = rowb + ai * HALF + m * 16; const float r = rt[ai * HALF + wr * 64 + m * 16 + fr];
; #pragma unroll
;             for (int bj = 0; bj < 2; ++bj) { const int col = u.pn * BM + bj * HALF + wc * 32 + fq * 8;
;                 const f32x4 g0 = *(const f32x4*)(E.gfin + col), g1 = *(const f32x4*)(E.gfin + col + 4);
;                 __builtin_nontemporal_store(acc[ai][bj][m][0] * r * g0, (f32x4*)(E.yout + (size_t)row * 1024 + col));
;                 __builtin_nontemporal_store(acc[ai][bj][m][1] * r * g1, (f32x4*)(E.yout + (size_t)row * 1024 + col + 4)); } }
	v_pk_mul_f32 v[64:65], v[64:65], v[74:75] op_sel_hi:[1,0]
	v_pk_mul_f32 v[62:63], v[62:63], v[74:75] op_sel_hi:[1,0]
	v_pk_mul_f32 v[78:79], v[60:61], v[74:75] op_sel_hi:[1,0]
	v_pk_mul_f32 v[80:81], v[58:59], v[74:75] op_sel_hi:[1,0]
	v_pk_mul_f32 v[56:57], v[56:57], v[74:75] op_sel_hi:[1,0]
	v_pk_mul_f32 v[54:55], v[54:55], v[74:75] op_sel_hi:[1,0]
	v_pk_mul_f32 v[60:61], v[174:175], v[64:65]
	v_pk_mul_f32 v[58:59], v[172:173], v[62:63]
	v_pk_mul_f32 v[64:65], v[178:179], v[78:79]
	v_pk_mul_f32 v[62:63], v[176:177], v[80:81]
	v_mov_b32_e32 v232, v62
	v_mov_b32_e32 v233, v63
	v_mov_b32_e32 v234, v64
	v_mov_b32_e32 v235, v65
	v_mov_b32_dpp v232, v58 row_shl:8 row_mask:0xf bank_mask:0x3
	v_mov_b32_dpp v233, v59 row_shl:8 row_mask:0xf bank_mask:0x3
	v_mov_b32_dpp v234, v60 row_shl:8 row_mask:0xf bank_mask:0x3
	v_mov_b32_dpp v235, v61 row_shl:8 row_mask:0xf bank_mask:0x3
	v_mov_b32_dpp v58, v62 row_shr:8 row_mask:0xf bank_mask:0xc
	v_mov_b32_dpp v59, v63 row_shr:8 row_mask:0xf bank_mask:0xc
	v_mov_b32_dpp v60, v64 row_shr:8 row_mask:0xf bank_mask:0xc
	v_mov_b32_dpp v61, v65 row_shr:8 row_mask:0xf bank_mask:0xc
	v_lshl_add_u64 v[236:237], v[76:77], 0, v[240:241]
	v_lshl_add_u64 v[238:239], v[76:77], 0, v[242:243]
	global_store_dwordx4 v[236:237], v[58:61], off nt
	global_store_dwordx4 v[238:239], v[232:235], off nt
	v_pk_mul_f32 v[66:67], v[52:53], v[74:75] op_sel_hi:[1,0]
	v_pk_mul_f32 v[68:69], v[50:51], v[74:75] op_sel_hi:[1,0]
	v_pk_mul_f32 v[52:53], v[56:57], v[182:183]
	v_pk_mul_f32 v[50:51], v[54:55], v[180:181]
	v_pk_mul_f32 v[56:57], v[66:67], v[186:187]
	v_pk_mul_f32 v[54:55], v[68:69], v[184:185]
	v_mov_b32_e32 v232, v54
	v_mov_b32_e32 v233, v55
	v_mov_b32_e32 v234, v56
	v_mov_b32_e32 v235, v57
	v_mov_b32_dpp v232, v50 row_shl:8 row_mask:0xf bank_mask:0x3
	v_mov_b32_dpp v233, v51 row_shl:8 row_mask:0xf bank_mask:0x3
	v_mov_b32_dpp v234, v52 row_shl:8 row_mask:0xf bank_mask:0x3
	v_mov_b32_dpp v235, v53 row_shl:8 row_mask:0xf bank_mask:0x3
	v_mov_b32_dpp v50, v54 row_shr:8 row_mask:0xf bank_mask:0xc
	v_mov_b32_dpp v51, v55 row_shr:8 row_mask:0xf bank_mask:0xc
	v_mov_b32_dpp v52, v56 row_shr:8 row_mask:0xf bank_mask:0xc
	v_mov_b32_dpp v53, v57 row_shr:8 row_mask:0xf bank_mask:0xc
	v_lshl_add_u64 v[236:237], v[76:77], 0, v[240:241]
	v_lshl_add_u64 v[238:239], v[76:77], 0, v[242:243]
	global_store_dwordx4 v[236:237], v[50:53], off offset:512 nt
	global_store_dwordx4 v[238:239], v[232:235], off offset:512 nt
	v_lshlrev_b64 v[58:59], 12, v[142:143]
	v_mov_b32_e32 v60, v75
	v_lshl_add_u64 v[58:59], s[28:29], 0, v[58:59]
	v_pk_mul_f32 v[48:49], v[48:49], v[60:61] op_sel_hi:[1,0]
	v_pk_mul_f32 v[62:63], v[144:145], v[60:61] op_sel_hi:[1,0]
	v_lshl_add_u64 v[58:59], v[58:59], 0, v[148:149]
	v_pk_mul_f32 v[64:65], v[44:45], v[60:61] op_sel_hi:[1,0]
	v_pk_mul_f32 v[66:67], v[42:43], v[60:61] op_sel_hi:[1,0]
	v_pk_mul_f32 v[40:41], v[40:41], v[60:61] op_sel_hi:[1,0]
	v_pk_mul_f32 v[38:39], v[38:39], v[60:61] op_sel_hi:[1,0]
	v_pk_mul_f32 v[44:45], v[174:175], v[48:49]
	v_pk_mul_f32 v[42:43], v[172:173], v[62:63]
	v_pk_mul_f32 v[50:51], v[178:179], v[64:65]
	v_pk_mul_f32 v[48:49], v[176:177], v[66:67]
	v_mov_b32_e32 v232, v48
	v_mov_b32_e32 v233, v49
	v_mov_b32_e32 v234, v50
	v_mov_b32_e32 v235, v51
	v_mov_b32_dpp v232, v42 row_shl:8 row_mask:0xf bank_mask:0x3
	v_mov_b32_dpp v233, v43 row_shl:8 row_mask:0xf bank_mask:0x3
	v_mov_b32_dpp v234, v44 row_shl:8 row_mask:0xf bank_mask:0x3
	v_mov_b32_dpp v235, v45 row_shl:8 row_mask:0xf bank_mask:0x3
	v_mov_b32_dpp v42, v48 row_shr:8 row_mask:0xf bank_mask:0xc
	v_mov_b32_dpp v43, v49 row_shr:8 row_mask:0xf bank_mask:0xc
	v_mov_b32_dpp v44, v50 row_shr:8 row_mask:0xf bank_mask:0xc
	v_mov_b32_dpp v45, v51 row_shr:8 row_mask:0xf bank_mask:0xc
	v_lshl_add_u64 v[236:237], v[58:59], 0, v[240:241]
	v_lshl_add_u64 v[238:239], v[58:59], 0, v[242:243]
	global_store_dwordx4 v[236:237], v[42:45], off nt
	global_store_dwordx4 v[238:239], v[232:235], off nt
	v_pk_mul_f32 v[52:53], v[36:37], v[60:61] op_sel_hi:[1,0]
	v_pk_mul_f32 v[54:55], v[34:35], v[60:61] op_sel_hi:[1,0]
	v_pk_mul_f32 v[36:37], v[40:41], v[182:183]
	v_pk_mul_f32 v[34:35], v[38:39], v[180:181]
	v_pk_mul_f32 v[40:41], v[52:53], v[186:187]
	v_pk_mul_f32 v[38:39], v[54:55], v[184:185]
	v_mov_b32_e32 v232, v38
	v_mov_b32_e32 v233, v39
	v_mov_b32_e32 v234, v40
	v_mov_b32_e32 v235, v41
	v_mov_b32_dpp v232, v34 row_shl:8 row_mask:0xf bank_mask:0x3
	v_mov_b32_dpp v233, v35 row_shl:8 row_mask:0xf bank_mask:0x3
	v_mov_b32_dpp v234, v36 row_shl:8 row_mask:0xf bank_mask:0x3
	v_mov_b32_dpp v235, v37 row_shl:8 row_mask:0xf bank_mask:0x3
	v_mov_b32_dpp v34, v38 row_shr:8 row_mask:0xf bank_mask:0xc
	v_mov_b32_dpp v35, v39 row_shr:8 row_mask:0xf bank_mask:0xc
	v_mov_b32_dpp v36, v40 row_shr:8 row_mask:0xf bank_mask:0xc
	v_mov_b32_dpp v37, v41 row_shr:8 row_mask:0xf bank_mask:0xc
	v_lshl_add_u64 v[236:237], v[58:59], 0, v[240:241]
	v_lshl_add_u64 v[238:239], v[58:59], 0, v[242:243]
	global_store_dwordx4 v[236:237], v[34:37], off offset:512 nt
	global_store_dwordx4 v[238:239], v[232:235], off offset:512 nt
	ds_read2_b32 v[42:43], v1 offset0:160 offset1:176
	v_lshlrev_b64 v[44:45], 12, v[46:47]
	v_lshl_add_u64 v[44:45], s[28:29], 0, v[44:45]
	v_lshl_add_u64 v[44:45], v[44:45], 0, v[148:149]
	s_waitcnt lgkmcnt(0)
; __device__ __forceinline__ void epi_final(f32x4 (&acc)[2][2][4][2], const Unit& u, int wr, int wc, int fr, int fq, const EpiArgs& E, LAS float* rt) {
;     ...
;     for (int ai = 0; ai < 2; ++ai)
; #pragma unroll
;         for (int m = 0; m < 4; ++m) { const int row = rowb + ai * HALF + m * 16; const float r = rt[ai * HALF + wr * 64 + m * 16 + fr];
; #pragma unroll
;             for (int bj = 0; bj < 2; ++bj) { const int col = u.pn * BM + bj * HALF + wc * 32 + fq * 8;
;                 const f32x4 g0 = *(const f32x4*)(E.gfin + col), g1 = *(const f32x4*)(E.gfin + col + 4);
;                 __builtin_nontemporal_store(acc[ai][bj][m][0] * r * g0, (f32x4*)(E.yout + (size_t)row * 1024 + col));
;                 __builtin_nontemporal_store(acc[ai][bj][m][1] * r * g1, (f32x4*)(E.yout + (size_t)row * 1024 + col + 4)); } }
	v_pk_mul_f32 v[32:33], v[32:33], v[42:43] op_sel_hi:[1,0]
	v_pk_mul_f32 v[30:31], v[30:31], v[42:43] op_sel_hi:[1,0]
	v_pk_mul_f32 v[46:47], v[28:29], v[42:43] op_sel_hi:[1,0]
	v_pk_mul_f32 v[48:49], v[26:27], v[42:43] op_sel_hi:[1,0]
	v_pk_mul_f32 v[24:25], v[24:25], v[42:43] op_sel_hi:[1,0]
	v_pk_mul_f32 v[22:23], v[22:23], v[42:43] op_sel_hi:[1,0]
	v_pk_mul_f32 v[28:29], v[174:175], v[32:33]
	v_pk_mul_f32 v[26:27], v[172:173], v[30:31]
	v_pk_mul_f32 v[32:33], v[178:179], v[46:47]
	v_pk_mul_f32 v[30:31], v[176:177], v[48:49]
	v_mov_b32_e32 v232, v30
	v_mov_b32_e32 v233, v31
	v_mov_b32_e32 v234, v32
	v_mov_b32_e32 v235, v33
	v_mov_b32_dpp v232, v26 row_shl:8 row_mask:0xf bank_mask:0x3
	v_mov_b32_dpp v233, v27 row_shl:8 row_mask:0xf bank_mask:0x3
	v_mov_b32_dpp v234, v28 row_shl:8 row_mask:0xf bank_mask:0x3
	v_mov_b32_dpp v235, v29 row_shl:8 row_mask:0xf bank_mask:0x3
	v_mov_b32_dpp v26, v30 row_shr:8 row_mask:0xf bank_mask:0xc
	v_mov_b32_dpp v27, v31 row_shr:8 row_mask:0xf bank_mask:0xc
	v_mov_b32_dpp v28, v32 row_shr:8 row_mask:0xf bank_mask:0xc
	v_mov_b32_dpp v29, v33 row_shr:8 row_mask:0xf bank_mask:0xc
	v_lshl_add_u64 v[236:237], v[44:45], 0, v[240:241]
	v_lshl_add_u64 v[238:239], v[44:45], 0, v[242:243]
	global_store_dwordx4 v[236:237], v[26:29], off nt
	global_store_dwordx4 v[238:239], v[232:235], off nt
	v_pk_mul_f32 v[34:35], v[20:21], v[42:43] op_sel_hi:[1,0]
	v_pk_mul_f32 v[36:37], v[18:19], v[42:43] op_sel_hi:[1,0]
	v_pk_mul_f32 v[20:21], v[24:25], v[182:183]
	v_pk_mul_f32 v[18:19], v[22:23], v[180:181]
	v_pk_mul_f32 v[24:25], v[34:35], v[186:187]
	v_pk_mul_f32 v[22:23], v[36:37], v[184:185]
	v_mov_b32_e32 v232, v22
	v_mov_b32_e32 v233, v23
	v_mov_b32_e32 v234, v24
	v_mov_b32_e32 v235, v25
	v_mov_b32_dpp v232, v18 row_shl:8 row_mask:0xf bank_mask:0x3
	v_mov_b32_dpp v233, v19 row_shl:8 row_mask:0xf bank_mask:0x3
	v_mov_b32_dpp v234, v20 row_shl:8 row_mask:0xf bank_mask:0x3
	v_mov_b32_dpp v235, v21 row_shl:8 row_mask:0xf bank_mask:0x3
	v_mov_b32_dpp v18, v22 row_shr:8 row_mask:0xf bank_mask:0xc
	v_mov_b32_dpp v19, v23 row_shr:8 row_mask:0xf bank_mask:0xc
	v_mov_b32_dpp v20, v24 row_shr:8 row_mask:0xf bank_mask:0xc
	v_mov_b32_dpp v21, v25 row_shr:8 row_mask:0xf bank_mask:0xc
	v_lshl_add_u64 v[236:237], v[44:45], 0, v[240:241]
	v_lshl_add_u64 v[238:239], v[44:45], 0, v[242:243]
	global_store_dwordx4 v[236:237], v[18:21], off offset:512 nt
	global_store_dwordx4 v[238:239], v[232:235], off offset:512 nt
	v_lshlrev_b64 v[26:27], 12, v[146:147]
	v_mov_b32_e32 v28, v43
	v_lshl_add_u64 v[26:27], s[28:29], 0, v[26:27]
	v_pk_mul_f32 v[16:17], v[16:17], v[28:29] op_sel_hi:[1,0]
	v_pk_mul_f32 v[14:15], v[14:15], v[28:29] op_sel_hi:[1,0]
	v_lshl_add_u64 v[26:27], v[26:27], 0, v[148:149]
	v_pk_mul_f32 v[30:31], v[12:13], v[28:29] op_sel_hi:[1,0]
	v_pk_mul_f32 v[32:33], v[10:11], v[28:29] op_sel_hi:[1,0]
	v_pk_mul_f32 v[8:9], v[8:9], v[28:29] op_sel_hi:[1,0]
	v_pk_mul_f32 v[6:7], v[6:7], v[28:29] op_sel_hi:[1,0]
	v_pk_mul_f32 v[12:13], v[174:175], v[16:17]
	v_pk_mul_f32 v[10:11], v[172:173], v[14:15]
	v_pk_mul_f32 v[16:17], v[178:179], v[30:31]
	v_pk_mul_f32 v[14:15], v[176:177], v[32:33]
	v_mov_b32_e32 v232, v14
	v_mov_b32_e32 v233, v15
	v_mov_b32_e32 v234, v16
	v_mov_b32_e32 v235, v17
	v_mov_b32_dpp v232, v10 row_shl:8 row_mask:0xf bank_mask:0x3
	v_mov_b32_dpp v233, v11 row_shl:8 row_mask:0xf bank_mask:0x3
	v_mov_b32_dpp v234, v12 row_shl:8 row_mask:0xf bank_mask:0x3
	v_mov_b32_dpp v235, v13 row_shl:8 row_mask:0xf bank_mask:0x3
	v_mov_b32_dpp v10, v14 row_shr:8 row_mask:0xf bank_mask:0xc
	v_mov_b32_dpp v11, v15 row_shr:8 row_mask:0xf bank_mask:0xc
	v_mov_b32_dpp v12, v16 row_shr:8 row_mask:0xf bank_mask:0xc
	v_mov_b32_dpp v13, v17 row_shr:8 row_mask:0xf bank_mask:0xc
	v_lshl_add_u64 v[236:237], v[26:27], 0, v[240:241]
	v_lshl_add_u64 v[238:239], v[26:27], 0, v[242:243]
	global_store_dwordx4 v[236:237], v[10:13], off nt
	global_store_dwordx4 v[238:239], v[232:235], off nt
	v_pk_mul_f32 v[18:19], v[4:5], v[28:29] op_sel_hi:[1,0]
	v_pk_mul_f32 v[20:21], v[2:3], v[28:29] op_sel_hi:[1,0]
	v_pk_mul_f32 v[4:5], v[8:9], v[182:183]
	v_pk_mul_f32 v[2:3], v[6:7], v[180:181]
	v_pk_mul_f32 v[8:9], v[18:19], v[186:187]
	v_pk_mul_f32 v[6:7], v[20:21], v[184:185]
	v_mov_b32_e32 v232, v6
	v_mov_b32_e32 v233, v7
	v_mov_b32_e32 v234, v8
	v_mov_b32_e32 v235, v9
	v_mov_b32_dpp v232, v2 row_shl:8 row_mask:0xf bank_mask:0x3
	v_mov_b32_dpp v233, v3 row_shl:8 row_mask:0xf bank_mask:0x3
	v_mov_b32_dpp v234, v4 row_shl:8 row_mask:0xf bank_mask:0x3
	v_mov_b32_dpp v235, v5 row_shl:8 row_mask:0xf bank_mask:0x3
	v_mov_b32_dpp v2, v6 row_shr:8 row_mask:0xf bank_mask:0xc
	v_mov_b32_dpp v3, v7 row_shr:8 row_mask:0xf bank_mask:0xc
	v_mov_b32_dpp v4, v8 row_shr:8 row_mask:0xf bank_mask:0xc
	v_mov_b32_dpp v5, v9 row_shr:8 row_mask:0xf bank_mask:0xc
	v_lshl_add_u64 v[236:237], v[26:27], 0, v[240:241]
	v_lshl_add_u64 v[238:239], v[26:27], 0, v[242:243]
	global_store_dwordx4 v[236:237], v[2:5], off offset:512 nt
	global_store_dwordx4 v[238:239], v[232:235], off offset:512 nt
